# LN1 and LN2 phases: gain, bias, gate and modulation table vectors loaded together ahead of the reductions instead of one serial load-wait-store step per vector
# speedup vs baseline: 1.0508x; 1.0294x over previous
.LBB0_1178:
	s_or_b64 exec, exec, s[46:47]
	v_add_u32_e32 v0, 0xfffff000, v68
	v_lshlrev_b32_e32 v68, 16, v76
	v_and_b32_e32 v69, 0xffff0000, v76
	s_mov_b32 s0, 0x3fb504f3
	v_lshlrev_b32_e32 v76, 16, v77
	v_and_b32_e32 v77, 0xffff0000, v77
	v_pk_fma_f32 v[30:31], v[30:31], s[0:1], v[68:69] op_sel_hi:[1,0,1]
	v_lshlrev_b32_e32 v68, 16, v74
	v_and_b32_e32 v69, 0xffff0000, v74
	v_pk_fma_f32 v[32:33], v[32:33], s[0:1], v[76:77] op_sel_hi:[1,0,1]
	v_add_f32_e32 v53, v30, v31
	v_lshlrev_b32_e32 v74, 16, v75
	v_and_b32_e32 v75, 0xffff0000, v75
	v_pk_fma_f32 v[68:69], v[26:27], s[0:1], v[68:69] op_sel_hi:[1,0,1]
	v_add_f32_e32 v53, v53, v32
	v_pk_fma_f32 v[74:75], v[28:29], s[0:1], v[74:75] op_sel_hi:[1,0,1]
	v_add_f32_e32 v26, v68, v69
	v_add_f32_e32 v53, v33, v53
	v_add_f32_e32 v26, v26, v74
	v_add_f32_e32 v53, 0, v53
	v_add_f32_e32 v26, v75, v26
	v_add_f32_e32 v53, v53, v26
	v_lshlrev_b32_e32 v26, 16, v72
	v_and_b32_e32 v27, 0xffff0000, v72
	v_lshlrev_b32_e32 v28, 16, v73
	v_and_b32_e32 v29, 0xffff0000, v73
	v_pk_fma_f32 v[72:73], v[22:23], s[0:1], v[26:27] op_sel_hi:[1,0,1]
	v_pk_fma_f32 v[76:77], v[24:25], s[0:1], v[28:29] op_sel_hi:[1,0,1]
	v_add_f32_e32 v22, v72, v73
	v_add_f32_e32 v22, v22, v76
	v_add_f32_e32 v22, v77, v22
	v_add_f32_e32 v26, v53, v22
	v_lshlrev_b32_e32 v22, 16, v70
	v_and_b32_e32 v23, 0xffff0000, v70
	v_lshlrev_b32_e32 v24, 16, v71
	v_and_b32_e32 v25, 0xffff0000, v71
	v_pk_fma_f32 v[70:71], v[18:19], s[0:1], v[22:23] op_sel_hi:[1,0,1]
	v_lshrrev_b32_e32 v0, 11, v0
	v_pk_fma_f32 v[84:85], v[20:21], s[0:1], v[24:25] op_sel_hi:[1,0,1]
	v_add_f32_e32 v18, v70, v71
	v_add_u32_e32 v0, 1, v0
	v_add_f32_e32 v18, v18, v84
	v_readlane_b32 s48, v247, 49
	v_cndmask_b32_e32 v0, 0, v0, vcc
	v_add_f32_e32 v18, v85, v18
	v_readlane_b32 s50, v247, 51
	v_readlane_b32 s51, v247, 52
	v_add_u32_e32 v0, s68, v0
	s_and_b64 s[12:13], exec, s[38:39]
	v_add_f32_e32 v22, v26, v18
	v_mov_b64_e32 v[18:19], s[50:51]
	s_or_b64 s[42:43], s[12:13], s[42:43]
	v_mad_u64_u32 v[20:21], s[12:13], v0, s97, v[18:19]
	ds_bpermute_b32 v0, v35, v22
	s_mov_b64 s[12:13], 0x4000
	v_mov_b32_e32 v53, v1
	s_mov_b32 s0, 0x800000
	v_mov_b32_e32 v55, v1
	s_waitcnt lgkmcnt(0)
	v_add_f32_e32 v0, v22, v0
	ds_bpermute_b32 v18, v78, v0
	v_lshl_add_u64 v[22:23], v[50:51], 0, s[44:45]
	v_mov_b32_e32 v57, v1
	v_readlane_b32 s49, v247, 50
	v_readlane_b32 s52, v247, 53
	s_waitcnt lgkmcnt(0)
	v_add_f32_e32 v0, v0, v18
	ds_bpermute_b32 v18, v79, v0
	v_readlane_b32 s53, v247, 54
	v_readlane_b32 s54, v247, 55
	v_readlane_b32 s55, v247, 56
	v_readlane_b32 s56, v247, 57
	s_waitcnt lgkmcnt(0)
	v_add_f32_e32 v0, v0, v18
	ds_bpermute_b32 v18, v80, v0
	v_readlane_b32 s57, v247, 58
	v_readlane_b32 s58, v247, 59
	v_readlane_b32 s59, v247, 60
	v_readlane_b32 s60, v247, 61
	s_waitcnt lgkmcnt(0)
	v_add_f32_e32 v0, v0, v18
	ds_bpermute_b32 v18, v81, v0
	v_readlane_b32 s61, v247, 62
	v_readlane_b32 s62, v247, 63
	v_readlane_b32 s63, v246, 0
	s_waitcnt lgkmcnt(0)
	v_add_f32_e32 v0, v0, v18
	ds_bpermute_b32 v18, v82, v0
	s_waitcnt lgkmcnt(0)
	v_add_f32_e32 v0, v0, v18
	v_mul_f32_e32 v86, 0x3a800000, v0
	v_pk_add_f32 v[88:89], v[30:31], v[86:87] op_sel_hi:[1,0] neg_lo:[0,1] neg_hi:[0,1]
	global_load_dwordx4 v[24:27], v[36:37], off
	global_load_dwordx4 v[28:31], v[38:39], off
	v_pk_add_f32 v[94:95], v[68:69], v[86:87] op_sel_hi:[1,0] neg_lo:[0,1] neg_hi:[0,1]
	v_pk_add_f32 v[96:97], v[74:75], v[86:87] op_sel_hi:[1,0] neg_lo:[0,1] neg_hi:[0,1]
	v_mov_b32_e32 v74, v89
	v_mov_b32_e32 v75, v95
	v_pk_add_f32 v[102:103], v[72:73], v[86:87] op_sel_hi:[1,0] neg_lo:[0,1] neg_hi:[0,1]
	v_pk_add_f32 v[108:109], v[70:71], v[86:87] op_sel_hi:[1,0] neg_lo:[0,1] neg_hi:[0,1]
	v_pk_add_f32 v[32:33], v[32:33], v[86:87] op_sel_hi:[1,0] neg_lo:[0,1] neg_hi:[0,1]
	v_mov_b32_e32 v68, v88
	v_mov_b32_e32 v69, v94
	v_pk_mul_f32 v[74:75], v[74:75], v[74:75]
	v_mov_b32_e32 v72, v109
	v_mov_b32_e32 v73, v103
	v_pk_fma_f32 v[68:69], v[68:69], v[68:69], v[74:75]
	v_mov_b32_e32 v74, v32
	v_mov_b32_e32 v75, v96
	v_pk_add_f32 v[76:77], v[76:77], v[86:87] op_sel_hi:[1,0] neg_lo:[0,1] neg_hi:[0,1]
	v_pk_add_f32 v[110:111], v[84:85], v[86:87] op_sel_hi:[1,0] neg_lo:[0,1] neg_hi:[0,1]
	v_mov_b32_e32 v70, v108
	v_mov_b32_e32 v71, v102
	v_pk_mul_f32 v[72:73], v[72:73], v[72:73]
	v_lshl_add_u64 v[18:19], v[20:21], 0, s[12:13]
	s_mov_b64 s[12:13], 0x3000
	v_mov_b32_e32 v98, v33
	v_mov_b32_e32 v99, v97
	v_pk_fma_f32 v[68:69], v[74:75], v[74:75], v[68:69]
	v_pk_fma_f32 v[70:71], v[70:71], v[70:71], v[72:73]
	v_mov_b32_e32 v72, v110
	v_mov_b32_e32 v73, v76
	v_lshl_add_u64 v[20:21], v[20:21], 0, s[12:13]
	v_lshlrev_b32_e32 v0, 2, v34
	v_pk_fma_f32 v[68:69], v[98:99], v[98:99], v[68:69]
	v_mov_b32_e32 v74, v111
	v_mov_b32_e32 v75, v77
	v_pk_fma_f32 v[70:71], v[72:73], v[72:73], v[70:71]
	v_lshl_add_u64 v[90:91], v[18:19], 0, v[0:1]
	v_lshl_add_u64 v[92:93], v[20:21], 0, v[0:1]
	v_pk_fma_f32 v[70:71], v[74:75], v[74:75], v[70:71]
	v_add_f32_e32 v0, v68, v69
	v_add_f32_e32 v0, v71, v0
	v_add_f32_e32 v0, v70, v0
	v_lshl_add_u64 v[98:99], v[18:19], 0, v[52:53]
	v_lshl_add_u64 v[100:101], v[20:21], 0, v[52:53]
	ds_bpermute_b32 v53, v35, v0
	v_lshl_add_u64 v[104:105], v[18:19], 0, v[54:55]
	v_lshl_add_u64 v[106:107], v[20:21], 0, v[54:55]
	v_lshl_add_u64 v[18:19], v[18:19], 0, v[56:57]
	global_load_dwordx4 v[112:115], v[90:91], off
	global_load_dwordx4 v[116:119], v[92:93], off
	global_load_dwordx4 v[120:123], v[36:37], off offset:1024
	global_load_dwordx4 v[124:127], v[38:39], off offset:1024
	global_load_dwordx4 v[128:131], v[98:99], off
	global_load_dwordx4 v[132:135], v[100:101], off
	global_load_dwordx4 v[136:139], v[36:37], off offset:2048
	global_load_dwordx4 v[160:163], v[38:39], off offset:2048
	global_load_dwordx4 v[164:167], v[104:105], off
	global_load_dwordx4 v[168:171], v[106:107], off
	global_load_dwordx4 v[172:175], v[36:37], off offset:3072
	global_load_dwordx4 v[176:179], v[38:39], off offset:3072
	global_load_dwordx4 v[216:219], v[18:19], off
	v_lshl_add_u64 v[224:225], v[20:21], 0, v[56:57]
	global_load_dwordx4 v[220:223], v[224:225], off
	s_waitcnt lgkmcnt(0)
	v_add_f32_e32 v0, v0, v53
	ds_bpermute_b32 v53, v78, v0
	s_waitcnt lgkmcnt(0)
	v_add_f32_e32 v0, v0, v53
	ds_bpermute_b32 v53, v79, v0
	s_waitcnt lgkmcnt(0)
	v_add_f32_e32 v0, v0, v53
	ds_bpermute_b32 v53, v80, v0
	s_waitcnt lgkmcnt(0)
	v_add_f32_e32 v0, v0, v53
	ds_bpermute_b32 v53, v81, v0
	s_waitcnt lgkmcnt(0)
	v_add_f32_e32 v0, v0, v53
	ds_bpermute_b32 v53, v82, v0
	s_waitcnt lgkmcnt(0)
	v_add_f32_e32 v0, v0, v53
	v_fmamk_f32 v0, v0, 0x3a800000, v210
	v_cmp_gt_f32_e32 vcc, s0, v0
	v_mul_f32_e32 v53, 0x4b800000, v0
	s_nop 0
	v_cndmask_b32_e32 v0, v0, v53, vcc
	v_rsq_f32_e32 v0, v0
	s_nop 0
	v_mul_f32_e32 v53, 0x45800000, v0
	v_cndmask_b32_e32 v0, v0, v53, vcc
	v_pk_mul_f32 v[68:69], v[88:89], v[0:1] op_sel_hi:[1,0]
	s_waitcnt vmcnt(0)
	v_pk_fma_f32 v[28:29], v[24:25], v[68:69], v[28:29]
	v_pk_mul_f32 v[24:25], v[32:33], v[0:1] op_sel_hi:[1,0]
	s_nop 0
	v_pk_fma_f32 v[30:31], v[26:27], v[24:25], v[30:31]
	global_store_dwordx4 v[22:23], v[28:31], off
	v_pk_add_f32 v[24:25], v[112:113], 1.0 op_sel_hi:[1,0]
	s_nop 0
	v_pk_fma_f32 v[26:27], v[24:25], v[28:29], v[116:117]
	v_pk_add_f32 v[24:25], v[114:115], 1.0 op_sel_hi:[1,0]
	s_nop 0
	v_pk_fma_f32 v[28:29], v[24:25], v[30:31], v[118:119]
	v_cvt_pk_bf16_f32 v24, v26, v27
	v_cvt_pk_bf16_f32 v25, v28, v29
	global_store_dwordx2 v[44:45], v[24:25], off
	v_pk_mul_f32 v[24:25], v[94:95], v[0:1] op_sel_hi:[1,0]
	s_nop 0
	v_pk_fma_f32 v[30:31], v[24:25], v[120:121], v[124:125]
	v_pk_mul_f32 v[24:25], v[96:97], v[0:1] op_sel_hi:[1,0]
	s_nop 0
	v_pk_fma_f32 v[32:33], v[24:25], v[122:123], v[126:127]
	global_store_dwordx4 v[22:23], v[30:33], off offset:1024
	v_pk_add_f32 v[24:25], v[128:129], 1.0 op_sel_hi:[1,0]
	s_nop 1
	v_pk_fma_f32 v[30:31], v[30:31], v[24:25], v[132:133]
	v_pk_add_f32 v[24:25], v[130:131], 1.0 op_sel_hi:[1,0]
	s_nop 0
	v_pk_fma_f32 v[32:33], v[32:33], v[24:25], v[134:135]
	v_cvt_pk_bf16_f32 v24, v30, v31
	v_cvt_pk_bf16_f32 v25, v32, v33
	global_store_dwordx2 v[44:45], v[24:25], off offset:512
	v_pk_mul_f32 v[24:25], v[102:103], v[0:1] op_sel_hi:[1,0]
	s_nop 0
	v_pk_fma_f32 v[68:69], v[24:25], v[136:137], v[160:161]
	v_pk_mul_f32 v[24:25], v[76:77], v[0:1] op_sel_hi:[1,0]
	s_nop 0
	v_pk_fma_f32 v[70:71], v[24:25], v[138:139], v[162:163]
	global_store_dwordx4 v[22:23], v[68:71], off offset:2048
	v_pk_add_f32 v[24:25], v[164:165], 1.0 op_sel_hi:[1,0]
	s_nop 1
	v_pk_fma_f32 v[68:69], v[68:69], v[24:25], v[168:169]
	v_pk_add_f32 v[24:25], v[166:167], 1.0 op_sel_hi:[1,0]
	s_nop 0
	v_pk_fma_f32 v[70:71], v[70:71], v[24:25], v[170:171]
	v_cvt_pk_bf16_f32 v24, v68, v69
	v_cvt_pk_bf16_f32 v25, v70, v71
	global_store_dwordx2 v[44:45], v[24:25], off offset:1024
	v_pk_mul_f32 v[24:25], v[108:109], v[0:1] op_sel_hi:[1,0]
	s_nop 0
	v_pk_fma_f32 v[84:85], v[24:25], v[172:173], v[176:177]
	v_pk_mul_f32 v[24:25], v[110:111], v[0:1] op_sel_hi:[1,0]
	s_nop 0
	v_pk_fma_f32 v[86:87], v[24:25], v[174:175], v[178:179]
	global_store_dwordx4 v[22:23], v[84:87], off offset:3072
	v_pk_add_f32 v[18:19], v[216:217], 1.0 op_sel_hi:[1,0]
	s_nop 1
	v_pk_fma_f32 v[74:75], v[84:85], v[18:19], v[220:221]
	v_pk_add_f32 v[18:19], v[218:219], 1.0 op_sel_hi:[1,0]
	s_nop 0
	v_pk_fma_f32 v[72:73], v[86:87], v[18:19], v[222:223]
	v_cvt_pk_bf16_f32 v18, v74, v75
	v_cvt_pk_bf16_f32 v19, v72, v73
	global_store_dwordx2 v[44:45], v[18:19], off offset:1536
	ds_read_b128 v[18:21], v83
	s_waitcnt lgkmcnt(0)
	v_mul_f32_e32 v0, v27, v19
	v_fmac_f32_e32 v0, v26, v18
	v_fmac_f32_e32 v0, v28, v20
	v_fmac_f32_e32 v0, v29, v21
	ds_read_b128 v[18:21], v83 offset:1024
	v_add_f32_e32 v0, 0, v0
	s_waitcnt lgkmcnt(0)
	v_mul_f32_e32 v19, v31, v19
	v_fmac_f32_e32 v19, v30, v18
	v_fmac_f32_e32 v19, v32, v20
	v_fmac_f32_e32 v19, v33, v21
	v_add_f32_e32 v0, v0, v19
	ds_read_b128 v[18:21], v83 offset:2048
	s_waitcnt lgkmcnt(0)
	v_mul_f32_e32 v19, v69, v19
	v_fmac_f32_e32 v19, v68, v18
	v_fmac_f32_e32 v19, v70, v20
	v_fmac_f32_e32 v19, v71, v21
	v_add_f32_e32 v0, v0, v19
	ds_read_b128 v[18:21], v83 offset:3072
	s_waitcnt lgkmcnt(0)
	v_mul_f32_e32 v19, v75, v19
	v_fmac_f32_e32 v19, v74, v18
	v_fmac_f32_e32 v19, v72, v20
	v_fmac_f32_e32 v19, v73, v21
	v_add_f32_e32 v0, v0, v19
	ds_read_b128 v[18:21], v83 offset:7168
	ds_read_b128 v[22:25], v83 offset:6144
	ds_read_b128 v[84:87], v83 offset:5120
	ds_read_b128 v[88:91], v83 offset:4096
	s_waitcnt lgkmcnt(3)
	v_mul_f32_e32 v18, v74, v18
	s_waitcnt lgkmcnt(2)
	v_mul_f32_e32 v22, v68, v22
	s_waitcnt lgkmcnt(1)
	v_mul_f32_e32 v55, v30, v84
	s_waitcnt lgkmcnt(0)
	v_mul_f32_e32 v53, v26, v88
	v_fmac_f32_e32 v53, v27, v89
	v_fmac_f32_e32 v53, v28, v90
	v_fmac_f32_e32 v55, v31, v85
	v_fmac_f32_e32 v53, v29, v91
	v_fmac_f32_e32 v55, v32, v86
	v_fmac_f32_e32 v22, v69, v23
	v_add_f32_e32 v53, 0, v53
	v_fmac_f32_e32 v55, v33, v87
	v_fmac_f32_e32 v22, v70, v24
	v_fmac_f32_e32 v18, v75, v19
	v_add_f32_e32 v53, v55, v53
	v_fmac_f32_e32 v22, v71, v25
	v_fmac_f32_e32 v18, v72, v20
	v_add_f32_e32 v22, v22, v53
	v_fmac_f32_e32 v18, v73, v21
	v_add_f32_e32 v53, v18, v22
	ds_read_b128 v[18:21], v83 offset:11264
	ds_read_b128 v[22:25], v83 offset:10240
	ds_read_b128 v[84:87], v83 offset:9216
	ds_read_b128 v[88:91], v83 offset:8192
	s_waitcnt lgkmcnt(3)
	v_mul_f32_e32 v18, v74, v18
	s_waitcnt lgkmcnt(2)
	v_mul_f32_e32 v22, v68, v22
	s_waitcnt lgkmcnt(1)
	v_mul_f32_e32 v57, v30, v84
	s_waitcnt lgkmcnt(0)
	v_mul_f32_e32 v55, v26, v88
	v_fmac_f32_e32 v55, v27, v89
	v_fmac_f32_e32 v55, v28, v90
	v_fmac_f32_e32 v57, v31, v85
	v_fmac_f32_e32 v55, v29, v91
	v_fmac_f32_e32 v57, v32, v86
	v_fmac_f32_e32 v22, v69, v23
	v_add_f32_e32 v55, 0, v55
	v_fmac_f32_e32 v57, v33, v87
	v_fmac_f32_e32 v22, v70, v24
	v_fmac_f32_e32 v18, v75, v19
	v_add_f32_e32 v55, v57, v55
	v_fmac_f32_e32 v22, v71, v25
	v_fmac_f32_e32 v18, v72, v20
	v_add_f32_e32 v22, v22, v55
	v_fmac_f32_e32 v18, v73, v21
	v_add_f32_e32 v55, v18, v22
	ds_read_b128 v[18:21], v83 offset:15360
	ds_read_b128 v[22:25], v83 offset:14336
	ds_read_b128 v[84:87], v83 offset:13312
	ds_read_b128 v[88:91], v83 offset:12288
	s_waitcnt lgkmcnt(3)
	v_mul_f32_e32 v18, v74, v18
	s_waitcnt lgkmcnt(2)
	v_mul_f32_e32 v22, v68, v22
	s_waitcnt lgkmcnt(1)
	v_mul_f32_e32 v59, v30, v84
	s_waitcnt lgkmcnt(0)
	v_mul_f32_e32 v57, v26, v88
	v_fmac_f32_e32 v57, v27, v89
	v_fmac_f32_e32 v57, v28, v90
	v_fmac_f32_e32 v59, v31, v85
	v_fmac_f32_e32 v57, v29, v91
	v_fmac_f32_e32 v59, v32, v86
	v_fmac_f32_e32 v22, v69, v23
	v_add_f32_e32 v57, 0, v57
	v_fmac_f32_e32 v59, v33, v87
	v_fmac_f32_e32 v22, v70, v24
	v_fmac_f32_e32 v18, v75, v19
	v_add_f32_e32 v57, v59, v57
	v_fmac_f32_e32 v22, v71, v25
	v_fmac_f32_e32 v18, v72, v20
	v_add_f32_e32 v22, v22, v57
	v_fmac_f32_e32 v18, v73, v21
	v_add_f32_e32 v18, v18, v22
	ds_read_b128 v[20:23], v83 offset:16384
	ds_read_b128 v[84:87], v83 offset:17408
	ds_read_b128 v[88:91], v83 offset:18432
	s_waitcnt lgkmcnt(2)
	v_mul_f32_e32 v19, v27, v21
	s_waitcnt lgkmcnt(1)
	v_mul_f32_e32 v21, v31, v85
	v_fmac_f32_e32 v19, v26, v20
	v_fmac_f32_e32 v21, v30, v84
	v_fmac_f32_e32 v19, v28, v22
	v_fmac_f32_e32 v19, v29, v23
	v_fmac_f32_e32 v21, v32, v86
	v_add_f32_e32 v19, 0, v19
	v_fmac_f32_e32 v21, v33, v87
	v_add_f32_e32 v19, v19, v21
	ds_read_b128 v[20:23], v83 offset:19456
	s_waitcnt lgkmcnt(1)
	v_mul_f32_e32 v24, v69, v89
	v_fmac_f32_e32 v24, v68, v88
	v_fmac_f32_e32 v24, v70, v90
	v_fmac_f32_e32 v24, v71, v91
	ds_read_b128 v[84:87], v83 offset:21504
	ds_read_b128 v[88:91], v83 offset:20480
	s_waitcnt lgkmcnt(2)
	v_mul_f32_e32 v21, v75, v21
	v_fmac_f32_e32 v21, v74, v20
	v_fmac_f32_e32 v21, v72, v22
	v_add_f32_e32 v19, v19, v24
	v_fmac_f32_e32 v21, v73, v23
	v_add_f32_e32 v19, v19, v21
	ds_read_b128 v[20:23], v83 offset:23552
	ds_read_b128 v[92:95], v83 offset:22528
	s_waitcnt lgkmcnt(2)
	v_mul_f32_e32 v24, v26, v88
	v_fmac_f32_e32 v24, v27, v89
	v_mul_f32_e32 v25, v30, v84
	v_fmac_f32_e32 v24, v28, v90
	v_fmac_f32_e32 v25, v31, v85
	v_fmac_f32_e32 v24, v29, v91
	v_fmac_f32_e32 v25, v32, v86
	v_add_f32_e32 v24, 0, v24
	v_fmac_f32_e32 v25, v33, v87
	v_add_f32_e32 v24, v25, v24
	s_waitcnt lgkmcnt(0)
	v_mul_f32_e32 v25, v68, v92
	ds_read_b128 v[84:87], v83 offset:25600
	ds_read_b128 v[88:91], v83 offset:24576
	v_fmac_f32_e32 v25, v69, v93
	v_mul_f32_e32 v20, v74, v20
	v_fmac_f32_e32 v25, v70, v94
	v_fmac_f32_e32 v20, v75, v21
	v_fmac_f32_e32 v25, v71, v95
	v_fmac_f32_e32 v20, v72, v22
	v_add_f32_e32 v24, v25, v24
	v_fmac_f32_e32 v20, v73, v23
	v_add_f32_e32 v24, v20, v24
	ds_read_b128 v[20:23], v83 offset:27648
	ds_read_b128 v[92:95], v83 offset:26624
	s_waitcnt lgkmcnt(2)
	v_mul_f32_e32 v25, v26, v88
	v_fmac_f32_e32 v25, v27, v89
	v_mul_f32_e32 v57, v30, v84
	v_fmac_f32_e32 v25, v28, v90
	v_fmac_f32_e32 v57, v31, v85
	v_fmac_f32_e32 v25, v29, v91
	v_fmac_f32_e32 v57, v32, v86
	v_add_f32_e32 v25, 0, v25
	v_fmac_f32_e32 v57, v33, v87
	v_add_f32_e32 v25, v57, v25
	s_waitcnt lgkmcnt(0)
	v_mul_f32_e32 v57, v68, v92
	ds_read_b128 v[84:87], v83 offset:29696
	ds_read_b128 v[88:91], v83 offset:28672
	v_fmac_f32_e32 v57, v69, v93
	v_mul_f32_e32 v20, v74, v20
	v_fmac_f32_e32 v57, v70, v94
	v_fmac_f32_e32 v20, v75, v21
	v_fmac_f32_e32 v57, v71, v95
	v_fmac_f32_e32 v20, v72, v22
	v_add_f32_e32 v25, v57, v25
	v_fmac_f32_e32 v20, v73, v23
	v_add_f32_e32 v25, v20, v25
	ds_read_b128 v[20:23], v83 offset:31744
	ds_read_b128 v[92:95], v83 offset:30720
	s_waitcnt lgkmcnt(2)
	v_mul_f32_e32 v57, v26, v88
	v_fmac_f32_e32 v57, v27, v89
	v_mul_f32_e32 v59, v30, v84
	v_fmac_f32_e32 v57, v28, v90
	v_fmac_f32_e32 v59, v31, v85
	v_fmac_f32_e32 v57, v29, v91
	v_fmac_f32_e32 v59, v32, v86
	v_add_f32_e32 v57, 0, v57
	v_fmac_f32_e32 v59, v33, v87
	v_add_f32_e32 v57, v59, v57
	s_waitcnt lgkmcnt(0)
	v_mul_f32_e32 v59, v68, v92
	v_fmac_f32_e32 v59, v69, v93
	v_mul_f32_e32 v20, v74, v20
	v_fmac_f32_e32 v59, v70, v94
	v_fmac_f32_e32 v20, v75, v21
	v_fmac_f32_e32 v59, v71, v95
	v_fmac_f32_e32 v20, v72, v22
	v_add_f32_e32 v57, v59, v57
	v_fmac_f32_e32 v20, v73, v23
	v_add_f32_e32 v57, v20, v57
	ds_read_b128 v[20:23], v83 offset:32768
	ds_read_b128 v[84:87], v83 offset:33792
	ds_read_b128 v[88:91], v83 offset:34816
	s_waitcnt lgkmcnt(2)
	v_mul_f32_e32 v21, v27, v21
	s_waitcnt lgkmcnt(1)
	v_mul_f32_e32 v59, v31, v85
	v_fmac_f32_e32 v21, v26, v20
	v_fmac_f32_e32 v59, v30, v84
	v_fmac_f32_e32 v21, v28, v22
	v_fmac_f32_e32 v21, v29, v23
	v_fmac_f32_e32 v59, v32, v86
	v_add_f32_e32 v20, 0, v21
	v_fmac_f32_e32 v59, v33, v87
	v_add_f32_e32 v59, v20, v59
	ds_read_b128 v[20:23], v83 offset:35840
	s_waitcnt lgkmcnt(1)
	v_mul_f32_e32 v76, v69, v89
	v_fmac_f32_e32 v76, v68, v88
	v_fmac_f32_e32 v76, v70, v90
	v_fmac_f32_e32 v76, v71, v91
	ds_read_b128 v[84:87], v83 offset:37888
	ds_read_b128 v[88:91], v83 offset:36864
	s_waitcnt lgkmcnt(2)
	v_mul_f32_e32 v21, v75, v21
	v_fmac_f32_e32 v21, v74, v20
	v_fmac_f32_e32 v21, v72, v22
	v_add_f32_e32 v59, v59, v76
	v_fmac_f32_e32 v21, v73, v23
	v_add_f32_e32 v59, v59, v21
	ds_read_b128 v[20:23], v83 offset:39936
	ds_read_b128 v[92:95], v83 offset:38912
	s_waitcnt lgkmcnt(2)
	v_mul_f32_e32 v76, v26, v88
	v_fmac_f32_e32 v76, v27, v89
	v_mul_f32_e32 v77, v30, v84
	v_fmac_f32_e32 v76, v28, v90
	v_fmac_f32_e32 v77, v31, v85
	v_fmac_f32_e32 v76, v29, v91
	v_fmac_f32_e32 v77, v32, v86
	v_add_f32_e32 v76, 0, v76
	v_fmac_f32_e32 v77, v33, v87
	v_add_f32_e32 v76, v77, v76
	s_waitcnt lgkmcnt(0)
	v_mul_f32_e32 v77, v68, v92
	ds_read_b128 v[84:87], v83 offset:41984
	ds_read_b128 v[88:91], v83 offset:40960
	v_fmac_f32_e32 v77, v69, v93
	v_mul_f32_e32 v20, v74, v20
	v_fmac_f32_e32 v77, v70, v94
	v_fmac_f32_e32 v20, v75, v21
	v_fmac_f32_e32 v77, v71, v95
	v_fmac_f32_e32 v20, v72, v22
	v_add_f32_e32 v76, v77, v76
	v_fmac_f32_e32 v20, v73, v23
	v_add_f32_e32 v76, v20, v76
	ds_read_b128 v[20:23], v83 offset:44032
	ds_read_b128 v[92:95], v83 offset:43008
	s_waitcnt lgkmcnt(2)
	v_mul_f32_e32 v77, v26, v88
	v_fmac_f32_e32 v77, v27, v89
	v_mul_f32_e32 v84, v30, v84
	v_fmac_f32_e32 v77, v28, v90
	v_fmac_f32_e32 v84, v31, v85
	v_fmac_f32_e32 v77, v29, v91
	v_fmac_f32_e32 v84, v32, v86
	v_add_f32_e32 v77, 0, v77
	v_fmac_f32_e32 v84, v33, v87
	v_add_f32_e32 v77, v84, v77
	s_waitcnt lgkmcnt(0)
	v_mul_f32_e32 v84, v68, v92
	v_fmac_f32_e32 v84, v69, v93
	v_fmac_f32_e32 v84, v70, v94
	v_mul_f32_e32 v20, v74, v20
	v_fmac_f32_e32 v84, v71, v95
	v_fmac_f32_e32 v20, v75, v21
	v_add_f32_e32 v77, v84, v77
	v_fmac_f32_e32 v20, v72, v22
	ds_read_b128 v[84:87], v83 offset:46080
	ds_read_b128 v[88:91], v83 offset:45056
	v_fmac_f32_e32 v20, v73, v23
	v_add_f32_e32 v77, v20, v77
	ds_read_b128 v[20:23], v83 offset:48128
	ds_read_b128 v[92:95], v83 offset:47104
	s_waitcnt lgkmcnt(3)
	v_mul_f32_e32 v84, v30, v84
	s_waitcnt lgkmcnt(2)
	v_mul_f32_e32 v88, v26, v88
	v_fmac_f32_e32 v88, v27, v89
	v_fmac_f32_e32 v88, v28, v90
	v_fmac_f32_e32 v84, v31, v85
	s_waitcnt lgkmcnt(0)
	v_mul_f32_e32 v85, v68, v92
	v_fmac_f32_e32 v88, v29, v91
	v_fmac_f32_e32 v84, v32, v86
	v_fmac_f32_e32 v85, v69, v93
	v_mul_f32_e32 v20, v74, v20
	v_add_f32_e32 v88, 0, v88
	v_fmac_f32_e32 v84, v33, v87
	v_fmac_f32_e32 v85, v70, v94
	v_fmac_f32_e32 v20, v75, v21
	v_add_f32_e32 v84, v84, v88
	v_fmac_f32_e32 v85, v71, v95
	v_fmac_f32_e32 v20, v72, v22
	v_add_f32_e32 v84, v85, v84
	v_fmac_f32_e32 v20, v73, v23
	v_add_f32_e32 v96, v20, v84
	ds_read_b128 v[20:23], v83 offset:49152
	ds_read_b128 v[84:87], v83 offset:50176
	ds_read_b128 v[88:91], v83 offset:51200
	s_waitcnt lgkmcnt(2)
	v_mul_f32_e32 v21, v27, v21
	s_waitcnt lgkmcnt(1)
	v_mul_f32_e32 v85, v31, v85
	v_fmac_f32_e32 v21, v26, v20
	v_fmac_f32_e32 v85, v30, v84
	v_fmac_f32_e32 v21, v28, v22
	v_fmac_f32_e32 v21, v29, v23
	v_fmac_f32_e32 v85, v32, v86
	v_add_f32_e32 v20, 0, v21
	v_fmac_f32_e32 v85, v33, v87
	v_add_f32_e32 v84, v20, v85
	ds_read_b128 v[20:23], v83 offset:52224
	s_waitcnt lgkmcnt(1)
	v_mul_f32_e32 v85, v69, v89
	v_fmac_f32_e32 v85, v68, v88
	v_fmac_f32_e32 v85, v70, v90
	v_fmac_f32_e32 v85, v71, v91
	s_waitcnt lgkmcnt(0)
	v_mul_f32_e32 v21, v75, v21
	v_fmac_f32_e32 v21, v74, v20
	v_add_f32_e32 v92, v84, v85
	v_fmac_f32_e32 v21, v72, v22
	ds_read_b128 v[84:87], v83 offset:54272
	ds_read_b128 v[88:91], v83 offset:53248
	v_fmac_f32_e32 v21, v73, v23
	v_add_f32_e32 v97, v92, v21
	ds_read_b128 v[20:23], v83 offset:56320
	ds_read_b128 v[92:95], v83 offset:55296
	s_waitcnt lgkmcnt(3)
	v_mul_f32_e32 v84, v30, v84
	s_waitcnt lgkmcnt(2)
	v_mul_f32_e32 v88, v26, v88
	v_fmac_f32_e32 v88, v27, v89
	v_fmac_f32_e32 v88, v28, v90
	v_fmac_f32_e32 v84, v31, v85
	s_waitcnt lgkmcnt(0)
	v_mul_f32_e32 v85, v68, v92
	v_fmac_f32_e32 v88, v29, v91
	v_fmac_f32_e32 v84, v32, v86
	v_fmac_f32_e32 v85, v69, v93
	v_add_f32_e32 v88, 0, v88
	v_fmac_f32_e32 v84, v33, v87
	v_fmac_f32_e32 v85, v70, v94
	v_mul_f32_e32 v20, v74, v20
	v_add_f32_e32 v84, v84, v88
	v_fmac_f32_e32 v85, v71, v95
	v_fmac_f32_e32 v20, v75, v21
	v_add_f32_e32 v92, v85, v84
	v_fmac_f32_e32 v20, v72, v22
	ds_read_b128 v[84:87], v83 offset:58368
	ds_read_b128 v[88:91], v83 offset:57344
	v_fmac_f32_e32 v20, v73, v23
	v_add_f32_e32 v98, v20, v92
	ds_read_b128 v[20:23], v83 offset:60416
	ds_read_b128 v[92:95], v83 offset:59392
	s_waitcnt lgkmcnt(3)
	v_mul_f32_e32 v84, v30, v84
	s_waitcnt lgkmcnt(2)
	v_mul_f32_e32 v88, v26, v88
	v_fmac_f32_e32 v88, v27, v89
	v_fmac_f32_e32 v88, v28, v90
	v_fmac_f32_e32 v84, v31, v85
	s_waitcnt lgkmcnt(0)
	v_mul_f32_e32 v85, v68, v92
	v_fmac_f32_e32 v88, v29, v91
	v_fmac_f32_e32 v84, v32, v86
	v_fmac_f32_e32 v85, v69, v93
	v_add_f32_e32 v88, 0, v88
	v_fmac_f32_e32 v84, v33, v87
	v_fmac_f32_e32 v85, v70, v94
	v_add_f32_e32 v84, v84, v88
	v_fmac_f32_e32 v85, v71, v95
	v_add_f32_e32 v92, v85, v84
	ds_read_b128 v[84:87], v83 offset:62464
	ds_read_b128 v[88:91], v83 offset:61440
	v_mul_f32_e32 v20, v74, v20
	v_fmac_f32_e32 v20, v75, v21
	v_fmac_f32_e32 v20, v72, v22
	v_fmac_f32_e32 v20, v73, v23
	v_add_f32_e32 v99, v20, v92
	ds_read_b128 v[20:23], v83 offset:64512
	ds_read_b128 v[92:95], v83 offset:63488
	s_waitcnt lgkmcnt(2)
	v_mul_f32_e32 v26, v26, v88
	v_fmac_f32_e32 v26, v27, v89
	v_mul_f32_e32 v27, v30, v84
	v_fmac_f32_e32 v26, v28, v90
	v_fmac_f32_e32 v27, v31, v85
	v_fmac_f32_e32 v26, v29, v91
	v_fmac_f32_e32 v27, v32, v86
	v_add_f32_e32 v26, 0, v26
	v_fmac_f32_e32 v27, v33, v87
	v_add_f32_e32 v26, v27, v26
	s_waitcnt lgkmcnt(0)
	v_mul_f32_e32 v27, v68, v92
	v_fmac_f32_e32 v27, v69, v93
	v_mul_f32_e32 v20, v74, v20
	v_fmac_f32_e32 v27, v70, v94
	v_fmac_f32_e32 v20, v75, v21
	v_fmac_f32_e32 v27, v71, v95
	v_fmac_f32_e32 v20, v72, v22
	v_add_f32_e32 v26, v27, v26
	v_fmac_f32_e32 v20, v73, v23
	v_add_f32_e32 v20, v20, v26
	v_cndmask_b32_e64 v21, v0, v59, s[10:11]
	ds_bpermute_b32 v21, v35, v21
	v_cndmask_b32_e64 v0, v59, v0, s[10:11]
	v_cndmask_b32_e64 v22, v76, v53, s[10:11]
	v_cndmask_b32_e64 v23, v77, v55, s[10:11]
	s_waitcnt lgkmcnt(0)
	v_add_f32_e32 v0, v0, v21
	v_cndmask_b32_e64 v21, v53, v76, s[10:11]
	ds_bpermute_b32 v21, v35, v21
	s_waitcnt lgkmcnt(0)
	v_add_f32_e32 v21, v22, v21
	v_cndmask_b32_e64 v22, v55, v77, s[10:11]
	ds_bpermute_b32 v22, v35, v22
	s_waitcnt lgkmcnt(0)
	v_add_f32_e32 v22, v23, v22
	v_cndmask_b32_e64 v23, v18, v96, s[10:11]
	ds_bpermute_b32 v23, v35, v23
	v_cndmask_b32_e64 v18, v96, v18, s[10:11]
	s_waitcnt lgkmcnt(0)
	v_add_f32_e32 v18, v18, v23
	v_cndmask_b32_e64 v23, v19, v97, s[10:11]
	ds_bpermute_b32 v23, v35, v23
	v_cndmask_b32_e64 v19, v97, v19, s[10:11]
	s_waitcnt lgkmcnt(0)
	v_add_f32_e32 v19, v19, v23
	v_cndmask_b32_e64 v23, v24, v98, s[10:11]
	ds_bpermute_b32 v23, v35, v23
	v_cndmask_b32_e64 v24, v98, v24, s[10:11]
	s_waitcnt lgkmcnt(0)
	v_add_f32_e32 v23, v24, v23
	v_cndmask_b32_e64 v24, v25, v99, s[10:11]
	ds_bpermute_b32 v24, v35, v24
	v_cndmask_b32_e64 v25, v99, v25, s[10:11]
	s_waitcnt lgkmcnt(0)
	v_add_f32_e32 v24, v25, v24
	v_cndmask_b32_e64 v25, v57, v20, s[10:11]
	ds_bpermute_b32 v25, v35, v25
	v_cndmask_b32_e64 v20, v20, v57, s[10:11]
	s_waitcnt lgkmcnt(0)
	v_add_f32_e32 v20, v20, v25
	v_cndmask_b32_e64 v25, v0, v19, s[4:5]
	v_cndmask_b32_e64 v0, v19, v0, s[4:5]
	ds_bpermute_b32 v19, v78, v25
	s_waitcnt lgkmcnt(0)
	v_add_f32_e32 v0, v0, v19
	v_cndmask_b32_e64 v19, v21, v23, s[4:5]
	ds_bpermute_b32 v19, v78, v19
	v_cndmask_b32_e64 v21, v23, v21, s[4:5]
	s_waitcnt lgkmcnt(0)
	v_add_f32_e32 v19, v21, v19
	v_cndmask_b32_e64 v21, v22, v24, s[4:5]
	ds_bpermute_b32 v21, v78, v21
	v_cndmask_b32_e64 v22, v24, v22, s[4:5]
	s_waitcnt lgkmcnt(0)
	v_add_f32_e32 v21, v22, v21
	v_cndmask_b32_e64 v22, v18, v20, s[4:5]
	v_cndmask_b32_e64 v18, v20, v18, s[4:5]
	ds_bpermute_b32 v20, v78, v22
	s_waitcnt lgkmcnt(0)
	v_add_f32_e32 v18, v18, v20
	v_cndmask_b32_e64 v20, v0, v21, s[6:7]
	ds_bpermute_b32 v20, v79, v20
	v_cndmask_b32_e64 v0, v21, v0, s[6:7]
	s_waitcnt lgkmcnt(0)
	v_add_f32_e32 v0, v0, v20
	v_cndmask_b32_e64 v20, v19, v18, s[6:7]
	v_cndmask_b32_e64 v18, v18, v19, s[6:7]
	ds_bpermute_b32 v19, v79, v20
	s_waitcnt lgkmcnt(0)
	v_add_f32_e32 v18, v18, v19
	v_cndmask_b32_e64 v19, v0, v18, s[8:9]
	v_cndmask_b32_e64 v0, v18, v0, s[8:9]
	ds_bpermute_b32 v18, v80, v19
	s_waitcnt lgkmcnt(0)
	v_add_f32_e32 v0, v0, v18
	ds_bpermute_b32 v18, v81, v0
	s_waitcnt lgkmcnt(0)
	v_add_f32_e32 v0, v0, v18
	ds_bpermute_b32 v18, v82, v0
	s_waitcnt lgkmcnt(0)
	v_add_f32_e32 v0, v0, v18
	ds_bpermute_b32 v18, v35, v0
	s_waitcnt lgkmcnt(0)
	v_max_f32_e32 v18, v18, v18
	v_max_f32_e32 v18, v0, v18
	ds_bpermute_b32 v19, v78, v18
	s_waitcnt lgkmcnt(0)
	v_max_f32_e32 v19, v19, v19
	v_max_f32_e32 v18, v18, v19
	ds_bpermute_b32 v19, v79, v18
	s_waitcnt lgkmcnt(0)
	v_max_f32_e32 v19, v19, v19
	v_max_f32_e32 v18, v18, v19
	ds_bpermute_b32 v19, v80, v18
	s_waitcnt lgkmcnt(0)
	v_max_f32_e32 v19, v19, v19
	v_max_f32_e32 v18, v18, v19
	v_sub_f32_e32 v0, v0, v18
	v_mul_f32_e32 v0, 0x3fb8aa3b, v0
	v_exp_f32_e32 v0, v0
	ds_bpermute_b32 v18, v35, v0
	s_waitcnt lgkmcnt(0)
	v_add_f32_e32 v18, v0, v18
	ds_bpermute_b32 v19, v78, v18
	s_waitcnt lgkmcnt(0)
	v_add_f32_e32 v18, v18, v19
	ds_bpermute_b32 v19, v79, v18
	s_waitcnt lgkmcnt(0)
	v_add_f32_e32 v18, v18, v19
	ds_bpermute_b32 v19, v80, v18
	s_and_saveexec_b64 s[12:13], s[36:37]
	s_cbranch_execz .LBB0_1171
	s_waitcnt lgkmcnt(0)
	v_add_f32_e32 v18, v18, v19
	v_div_scale_f32 v19, s[38:39], v18, v18, v0
	v_rcp_f32_e32 v20, v19
	v_div_scale_f32 v21, vcc, v0, v18, v0
	v_readlane_b32 s48, v247, 49
	v_fma_f32 v22, -v19, v20, 1.0
	v_fmac_f32_e32 v20, v22, v20
	v_mul_f32_e32 v22, v21, v20
	v_fma_f32 v23, -v19, v22, v21
	v_fmac_f32_e32 v22, v23, v20
	v_fma_f32 v19, -v19, v22, v21
	v_div_fmas_f32 v19, v19, v20, v22
	v_readlane_b32 s60, v247, 61
	v_readlane_b32 s61, v247, 62
	v_div_fixup_f32 v0, v19, v18, v0
	v_readlane_b32 s49, v247, 50
	v_lshl_add_u64 v[18:19], s[60:61], 0, v[42:43]
	global_store_dword v[18:19], v0, off
	v_lshl_add_u64 v[18:19], s[92:93], 0, v[42:43]
	v_readlane_b32 s50, v247, 51
	v_readlane_b32 s51, v247, 52
	v_readlane_b32 s52, v247, 53
	v_readlane_b32 s53, v247, 54
	v_readlane_b32 s54, v247, 55
	v_readlane_b32 s55, v247, 56
	v_readlane_b32 s56, v247, 57
	v_readlane_b32 s57, v247, 58
	v_readlane_b32 s58, v247, 59
	v_readlane_b32 s59, v247, 60
	v_readlane_b32 s62, v247, 63
	v_readlane_b32 s63, v246, 0
	global_store_dword v[18:19], v211, off
	s_branch .LBB0_1171

.LBB0_1495:
	v_add_u32_e32 v0, 0xfffff000, v58
	v_lshrrev_b32_e32 v0, 11, v0
	v_add_u32_e32 v0, 1, v0
	v_readlane_b32 s36, v247, 49
	v_cndmask_b32_e64 v0, 0, v0, s[4:5]
	v_readlane_b32 s38, v247, 51
	v_readlane_b32 s39, v247, 52
	v_add_u32_e32 v41, s68, v0
	s_and_b64 s[4:5], exec, s[6:7]
	v_mov_b64_e32 v[76:77], s[38:39]
	s_movk_i32 s0, 0x6000
	s_or_b64 s[14:15], s[4:5], s[14:15]
	v_mad_u64_u32 v[78:79], s[4:5], v41, s0, v[76:77]
	v_add_u32_e32 v0, 5, v0
	s_mov_b64 s[4:5], 0x5000
	v_lshl_add_u64 v[82:83], v[78:79], 0, s[4:5]
	v_mad_u64_u32 v[76:77], s[4:5], v0, s0, v[76:77]
	v_mov_b32_e32 v41, v1
	v_lshlrev_b32_e32 v0, 2, v34
	v_lshlrev_b32_e32 v80, 2, v36
	v_mov_b32_e32 v81, v1
	v_lshlrev_b32_e32 v78, 2, v38
	v_mov_b32_e32 v79, v1
	v_lshl_add_u64 v[86:87], v[82:83], 0, v[40:41]
	v_lshl_add_u64 v[88:89], v[82:83], 0, v[0:1]
	v_lshl_add_u64 v[90:91], v[82:83], 0, v[80:81]
	v_lshl_add_u64 v[82:83], v[82:83], 0, v[78:79]
	global_load_dwordx4 v[112:115], v[82:83], off
	global_load_dwordx4 v[116:119], v[90:91], off
	global_load_dwordx4 v[120:123], v[88:89], off
	global_load_dwordx4 v[124:127], v[86:87], off
	s_mov_b32 s0, 0x3fb504f3
	s_mov_b64 s[4:5], 0x1000
	v_ashrrev_i32_e32 v59, 31, v58
	s_movk_i32 s97, 0x6000
	v_readlane_b32 s37, v247, 50
	v_readlane_b32 s40, v247, 53
	v_readlane_b32 s41, v247, 54
	v_readlane_b32 s42, v247, 55
	v_readlane_b32 s43, v247, 56
	v_readlane_b32 s44, v247, 57
	v_readlane_b32 s45, v247, 58
	v_readlane_b32 s46, v247, 59
	v_readlane_b32 s47, v247, 60
	v_readlane_b32 s48, v247, 61
	v_readlane_b32 s49, v247, 62
	v_readlane_b32 s50, v247, 63
	v_readlane_b32 s51, v246, 0
	s_waitcnt vmcnt(0)
	v_pk_mul_f32 v[72:73], v[72:73], v[114:115]
	s_nop 0
	v_pk_fma_f32 v[32:33], v[32:33], s[0:1], v[72:73] op_sel_hi:[1,0,1]
	v_pk_mul_f32 v[72:73], v[74:75], v[112:113]
	s_nop 0
	v_pk_fma_f32 v[72:73], v[30:31], s[0:1], v[72:73] op_sel_hi:[1,0,1]
	s_waitcnt vmcnt(0)
	v_pk_mul_f32 v[30:31], v[70:71], v[118:119]
	s_nop 0
	v_pk_fma_f32 v[70:71], v[28:29], s[0:1], v[30:31] op_sel_hi:[1,0,1]
	v_pk_mul_f32 v[28:29], v[68:69], v[116:117]
	v_lshlrev_b64 v[30:31], 10, v[58:59]
	v_pk_fma_f32 v[74:75], v[26:27], s[0:1], v[28:29] op_sel_hi:[1,0,1]
	v_mov_b32_e32 v27, v72
	v_mov_b32_e32 v26, v74
	v_mov_b32_e32 v28, v75
	v_mov_b32_e32 v29, v73
	v_pk_add_f32 v[26:27], v[26:27], v[28:29]
	v_mov_b32_e32 v28, v70
	v_mov_b32_e32 v29, v32
	v_pk_add_f32 v[26:27], v[26:27], v[28:29]
	v_mov_b32_e32 v28, v71
	v_mov_b32_e32 v29, v33
	v_pk_add_f32 v[68:69], v[26:27], v[28:29]
	s_nop 0
	s_waitcnt vmcnt(0)
	v_pk_mul_f32 v[28:29], v[66:67], v[122:123]
	s_nop 0
	v_pk_fma_f32 v[82:83], v[24:25], s[0:1], v[28:29] op_sel_hi:[1,0,1]
	v_pk_mul_f32 v[24:25], v[64:65], v[120:121]
	s_nop 0
	v_pk_fma_f32 v[84:85], v[22:23], s[0:1], v[24:25] op_sel_hi:[1,0,1]
	v_lshl_add_u64 v[28:29], v[76:77], 0, s[4:5]
	v_readlane_b32 s4, v245, 50
	v_readlane_b32 s5, v245, 51
	s_waitcnt vmcnt(0)
	v_pk_mul_f32 v[60:61], v[60:61], v[124:125]
	v_pk_mul_f32 v[22:23], v[62:63], v[126:127]
	v_pk_fma_f32 v[18:19], v[18:19], s[0:1], v[60:61] op_sel_hi:[1,0,1]
	v_pk_fma_f32 v[62:63], v[20:21], s[0:1], v[22:23] op_sel_hi:[1,0,1]
	v_mov_b32_e32 v60, v18
	v_mov_b32_e32 v61, v84
	v_mov_b32_e32 v64, v19
	v_mov_b32_e32 v65, v85
	v_pk_add_f32 v[60:61], v[60:61], v[64:65]
	v_mov_b32_e32 v64, v62
	v_mov_b32_e32 v65, v82
	v_pk_add_f32 v[60:61], v[60:61], v[64:65]
	v_mov_b32_e32 v64, v63
	v_mov_b32_e32 v65, v83
	v_pk_add_f32 v[60:61], v[60:61], v[64:65]
	global_load_dwordx4 v[20:23], v[42:43], off
	global_load_dwordx4 v[24:27], v[44:45], off
	global_load_dwordx4 v[128:131], v[42:43], off offset:1024
	global_load_dwordx4 v[132:135], v[44:45], off offset:1024
	global_load_dwordx4 v[136:139], v[42:43], off offset:2048
	global_load_dwordx4 v[160:163], v[44:45], off offset:2048
	global_load_dwordx4 v[164:167], v[42:43], off offset:3072
	global_load_dwordx4 v[168:171], v[44:45], off offset:3072
	v_lshl_add_u64 v[242:243], v[76:77], 0, v[40:41]
	v_lshl_add_u64 v[240:241], v[28:29], 0, v[40:41]
	global_load_dwordx4 v[172:175], v[240:241], off
	global_load_dwordx4 v[176:179], v[242:243], off
	v_lshl_add_u64 v[240:241], v[28:29], 0, v[0:1]
	global_load_dwordx4 v[216:219], v[240:241], off
	global_load_dwordx4 v[220:223], v[242:243], off offset:1024
	v_lshl_add_u64 v[240:241], v[28:29], 0, v[80:81]
	global_load_dwordx4 v[224:227], v[240:241], off
	global_load_dwordx4 v[228:231], v[242:243], off offset:2048
	v_lshl_add_u64 v[240:241], v[28:29], 0, v[78:79]
	global_load_dwordx4 v[232:235], v[240:241], off
	global_load_dwordx4 v[236:239], v[242:243], off offset:3072
	v_add_f32_e32 v57, 0, v60
	v_add_f32_e32 v57, v57, v61
	v_add_f32_e32 v57, v57, v68
	v_add_f32_e32 v57, v57, v69
	ds_bpermute_b32 v60, v37, v57
	s_mov_b32 s0, 0x800000
	s_waitcnt lgkmcnt(0)
	v_add_f32_e32 v57, v57, v60
	ds_bpermute_b32 v60, v39, v57
	s_waitcnt lgkmcnt(0)
	v_add_f32_e32 v57, v57, v60
	ds_bpermute_b32 v60, v100, v57
	s_waitcnt lgkmcnt(0)
	v_add_f32_e32 v57, v57, v60
	ds_bpermute_b32 v60, v101, v57
	s_waitcnt lgkmcnt(0)
	v_add_f32_e32 v57, v57, v60
	ds_bpermute_b32 v60, v102, v57
	s_waitcnt lgkmcnt(0)
	v_add_f32_e32 v57, v57, v60
	ds_bpermute_b32 v60, v103, v57
	s_waitcnt lgkmcnt(0)
	v_add_f32_e32 v57, v57, v60
	v_mul_f32_e32 v86, 0x3a800000, v57
	v_pk_add_f32 v[18:19], v[18:19], v[86:87] op_sel_hi:[1,0] neg_lo:[0,1] neg_hi:[0,1]
	v_pk_add_f32 v[68:69], v[84:85], v[86:87] op_sel_hi:[1,0] neg_lo:[0,1] neg_hi:[0,1]
	v_pk_add_f32 v[88:89], v[62:63], v[86:87] op_sel_hi:[1,0] neg_lo:[0,1] neg_hi:[0,1]
	v_mov_b32_e32 v62, v19
	v_mov_b32_e32 v63, v69
	v_pk_add_f32 v[66:67], v[82:83], v[86:87] op_sel_hi:[1,0] neg_lo:[0,1] neg_hi:[0,1]
	v_mov_b32_e32 v60, v18
	v_mov_b32_e32 v61, v68
	v_pk_mul_f32 v[62:63], v[62:63], v[62:63]
	v_pk_add_f32 v[64:65], v[74:75], v[86:87] op_sel_hi:[1,0] neg_lo:[0,1] neg_hi:[0,1]
	v_pk_fma_f32 v[60:61], v[60:61], v[60:61], v[62:63]
	v_mov_b32_e32 v62, v88
	v_mov_b32_e32 v63, v66
	v_pk_fma_f32 v[60:61], v[62:63], v[62:63], v[60:61]
	v_mov_b32_e32 v62, v89
	v_mov_b32_e32 v63, v67
	v_pk_fma_f32 v[82:83], v[62:63], v[62:63], v[60:61]
	v_pk_add_f32 v[60:61], v[72:73], v[86:87] op_sel_hi:[1,0] neg_lo:[0,1] neg_hi:[0,1]
	v_mov_b32_e32 v73, v65
	v_mov_b32_e32 v72, v61
	v_pk_add_f32 v[62:63], v[70:71], v[86:87] op_sel_hi:[1,0] neg_lo:[0,1] neg_hi:[0,1]
	v_pk_add_f32 v[32:33], v[32:33], v[86:87] op_sel_hi:[1,0] neg_lo:[0,1] neg_hi:[0,1]
	v_mov_b32_e32 v70, v60
	v_mov_b32_e32 v71, v64
	v_pk_mul_f32 v[72:73], v[72:73], v[72:73]
	v_add_f32_e32 v57, v82, v83
	v_pk_fma_f32 v[70:71], v[70:71], v[70:71], v[72:73]
	v_mov_b32_e32 v72, v32
	v_mov_b32_e32 v73, v62
	v_pk_fma_f32 v[70:71], v[72:73], v[72:73], v[70:71]
	v_mov_b32_e32 v72, v33
	v_mov_b32_e32 v73, v63
	v_pk_fma_f32 v[70:71], v[72:73], v[72:73], v[70:71]
	s_nop 0
	v_add_f32_e32 v57, v71, v57
	v_add_f32_e32 v57, v70, v57
	ds_bpermute_b32 v70, v37, v57
	s_waitcnt lgkmcnt(0)
	v_add_f32_e32 v57, v57, v70
	ds_bpermute_b32 v70, v39, v57
	s_waitcnt lgkmcnt(0)
	v_add_f32_e32 v57, v57, v70
	ds_bpermute_b32 v70, v100, v57
	s_waitcnt lgkmcnt(0)
	v_add_f32_e32 v57, v57, v70
	ds_bpermute_b32 v70, v101, v57
	s_waitcnt lgkmcnt(0)
	v_add_f32_e32 v57, v57, v70
	ds_bpermute_b32 v70, v102, v57
	s_waitcnt lgkmcnt(0)
	v_add_f32_e32 v57, v57, v70
	ds_bpermute_b32 v70, v103, v57
	s_waitcnt lgkmcnt(0)
	v_add_f32_e32 v57, v57, v70
	v_fmamk_f32 v57, v57, 0x3a800000, v210
	v_cmp_gt_f32_e32 vcc, s0, v57
	v_mul_f32_e32 v70, 0x4b800000, v57
	s_nop 0
	v_cndmask_b32_e32 v57, v57, v70, vcc
	v_rsq_f32_e32 v57, v57
	s_nop 0
	v_mul_f32_e32 v70, 0x45800000, v57
	v_cndmask_b32_e32 v70, v57, v70, vcc
	v_pk_mul_f32 v[18:19], v[18:19], v[70:71] op_sel_hi:[1,0]
	s_and_b64 vcc, exec, s[4:5]
	s_waitcnt vmcnt(0)
	v_pk_fma_f32 v[18:19], v[20:21], v[18:19], v[24:25]
	v_pk_mul_f32 v[20:21], v[88:89], v[70:71] op_sel_hi:[1,0]
	v_lshl_add_u64 v[24:25], v[30:31], 1, v[50:51]
	v_pk_fma_f32 v[20:21], v[22:23], v[20:21], v[26:27]
	v_lshlrev_b64 v[22:23], 12, v[58:59]
	v_lshl_add_u64 v[22:23], v[54:55], 0, v[22:23]
	global_store_dwordx4 v[22:23], v[18:21], off
	s_cbranch_vccz .LBB0_1497
	v_lshl_add_u64 v[26:27], v[28:29], 0, v[40:41]
	s_nop 0
	v_lshl_add_u64 v[26:27], v[76:77], 0, v[40:41]
	s_nop 0
	s_nop 0
	v_pk_add_f32 v[26:27], v[172:173], 1.0 op_sel_hi:[1,0]
	v_pk_add_f32 v[30:31], v[174:175], 1.0 op_sel_hi:[1,0]
	s_nop 0
	v_pk_fma_f32 v[18:19], v[18:19], v[26:27], v[176:177]
	v_pk_fma_f32 v[20:21], v[20:21], v[30:31], v[178:179]
	v_cvt_pk_bf16_f32 v18, v18, v19
	v_cvt_pk_bf16_f32 v19, v20, v21
	global_store_dwordx2 v[24:25], v[18:19], off
.LBB0_1497:
	s_nop 0
	s_nop 0
	s_nop 0
	v_mov_b32_e32 v71, v70
	v_pk_mul_f32 v[26:27], v[68:69], v[70:71]
	v_readlane_b32 s6, v245, 50
	v_readlane_b32 s7, v245, 51
	s_andn2_b64 vcc, exec, s[6:7]
	s_nop 0
	v_pk_fma_f32 v[18:19], v[26:27], v[128:129], v[132:133]
	v_pk_mul_f32 v[26:27], v[66:67], v[70:71]
	s_nop 0
	v_pk_fma_f32 v[20:21], v[26:27], v[130:131], v[134:135]
	v_cndmask_b32_e64 v26, 0, 1, s[6:7]
	v_cmp_ne_u32_e64 s[4:5], 1, v26
	global_store_dwordx4 v[22:23], v[18:21], off offset:1024
	s_cbranch_vccnz .LBB0_1499
	v_lshl_add_u64 v[26:27], v[28:29], 0, v[0:1]
	v_mov_b32_e32 v41, v1
	s_nop 0
	v_lshl_add_u64 v[26:27], v[76:77], 0, v[40:41]
	s_nop 0
	s_nop 0
	v_pk_add_f32 v[26:27], v[216:217], 1.0 op_sel_hi:[1,0]
	v_pk_add_f32 v[30:31], v[218:219], 1.0 op_sel_hi:[1,0]
	s_nop 0
	v_pk_fma_f32 v[18:19], v[18:19], v[26:27], v[220:221]
	v_pk_fma_f32 v[20:21], v[20:21], v[30:31], v[222:223]
	v_cvt_pk_bf16_f32 v18, v18, v19
	v_cvt_pk_bf16_f32 v19, v20, v21
	global_store_dwordx2 v[24:25], v[18:19], off offset:512
.LBB0_1499:
	s_nop 0
	s_nop 0
	s_nop 0
	v_pk_mul_f32 v[26:27], v[64:65], v[70:71]
	v_pk_mul_f32 v[30:31], v[62:63], v[70:71]
	s_and_b64 vcc, exec, s[4:5]
	s_nop 0
	v_pk_fma_f32 v[18:19], v[26:27], v[136:137], v[160:161]
	v_pk_fma_f32 v[20:21], v[30:31], v[138:139], v[162:163]
	global_store_dwordx4 v[22:23], v[18:21], off offset:2048
	s_cbranch_vccnz .LBB0_1501
	v_mov_b32_e32 v81, v1
	v_lshl_add_u64 v[26:27], v[28:29], 0, v[80:81]
	v_mov_b32_e32 v41, v1
	s_nop 0
	v_lshl_add_u64 v[26:27], v[76:77], 0, v[40:41]
	s_nop 0
	s_nop 0
	v_pk_add_f32 v[26:27], v[224:225], 1.0 op_sel_hi:[1,0]
	v_pk_add_f32 v[30:31], v[226:227], 1.0 op_sel_hi:[1,0]
	s_nop 0
	v_pk_fma_f32 v[18:19], v[18:19], v[26:27], v[228:229]
	v_pk_fma_f32 v[20:21], v[20:21], v[30:31], v[230:231]
	v_cvt_pk_bf16_f32 v18, v18, v19
	v_cvt_pk_bf16_f32 v19, v20, v21
	global_store_dwordx2 v[24:25], v[18:19], off offset:1024
.LBB0_1501:
	s_nop 0
	s_nop 0
	s_nop 0
	v_pk_mul_f32 v[26:27], v[60:61], v[70:71]
	v_pk_mul_f32 v[30:31], v[32:33], v[70:71]
	s_and_b64 vcc, exec, s[4:5]
	s_nop 0
	v_pk_fma_f32 v[18:19], v[26:27], v[164:165], v[168:169]
	v_pk_fma_f32 v[20:21], v[30:31], v[166:167], v[170:171]
	global_store_dwordx4 v[22:23], v[18:21], off offset:3072
	s_cbranch_vccnz .LBB0_1479
	v_mov_b32_e32 v79, v1
	v_lshl_add_u64 v[22:23], v[28:29], 0, v[78:79]
	v_mov_b32_e32 v41, v1
	s_nop 0
	v_lshl_add_u64 v[22:23], v[76:77], 0, v[40:41]
	s_nop 0
	s_nop 0
	v_pk_add_f32 v[22:23], v[232:233], 1.0 op_sel_hi:[1,0]
	v_pk_add_f32 v[26:27], v[234:235], 1.0 op_sel_hi:[1,0]
	s_nop 0
	v_pk_fma_f32 v[18:19], v[18:19], v[22:23], v[236:237]
	v_pk_fma_f32 v[20:21], v[20:21], v[26:27], v[238:239]
	v_cvt_pk_bf16_f32 v18, v18, v19
	v_cvt_pk_bf16_f32 v19, v20, v21
	global_store_dwordx2 v[24:25], v[18:19], off offset:1536
	s_branch .LBB0_1479
